# hand-written NA loop + context K/V fragments staged once per workgroup through LDS (each wave loads one 32-key block, all 8 read them back) (on top of v11)
# speedup vs baseline: 1.0108x; 1.0044x over previous
.LBB0_758:
	s_waitcnt vmcnt(0)
	v_readfirstlane_b32 s42, v188
	v_readfirstlane_b32 s43, v189
	v_readfirstlane_b32 s44, v190
	v_readfirstlane_b32 s45, v191
	v_readlane_b32 s0, v253, 34
	v_readlane_b32 s1, v251, 25
	v_readlane_b32 s13, v252, 14
	s_nop 3
	v_subrev_u32_e32 v174, s42, v188
	v_subrev_u32_e32 v175, s44, v190
	v_add_u32_e32 v176, 0x42000, v175
	v_add_u32_e32 v177, 0x84000, v175
	v_add_u32_e32 v178, 0xc6000, v175
	v_or_b32_e32 v3, s0, v187
	v_max_u32_e32 v3, 8, v3
	v_add_u32_e32 v3, -8, v3
	v_sub_u32_e32 v128, v180, v3
	v_add_u32_e32 v129, 32, v128
	v_or_b32_e32 v3, s1, v187
	v_add_u32_e32 v3, -8, v3
	v_min_u32_e32 v3, 48, v3
	v_sub_u32_e32 v130, v180, v3
	v_add_u32_e32 v131, 32, v130
	v_add_lshl_u32 v240, v233, v180, 2
	v_add_lshl_u32 v241, v231, v180, 2
	v_add_u32_e32 v240, 0x1e000, v240
	v_add_u32_e32 v241, 0x1e000, v241
	v_mov_b32_e32 v243, 0xff800000
	v_readfirstlane_b32 s14, v186
	v_and_b32_e32 v233, 63, v186
	v_lshlrev_b32_e32 v233, 4, v233
	s_lshr_b32 s14, s14, 6
	s_lshl_b32 vcc_lo, s14, 5
	s_lshl_b32 s0, vcc_lo, 9
	s_add_u32 s0, s42, s0
	s_addc_u32 s1, s43, 0
	global_load_dwordx4 v[112:115], v174, s[0:1]
	global_load_dwordx4 v[116:119], v174, s[0:1] offset:2048
	global_load_dwordx4 v[120:123], v174, s[0:1] offset:64
	global_load_dwordx4 v[124:127], v174, s[0:1] offset:2112
	s_lshl_b32 s0, vcc_lo, 1
	s_add_u32 s0, s44, s0
	s_addc_u32 s1, s45, 0
	global_load_dwordx4 v[80:83], v175, s[0:1]
	global_load_dwordx4 v[84:87], v176, s[0:1]
	global_load_dwordx4 v[88:91], v177, s[0:1]
	global_load_dwordx4 v[92:95], v178, s[0:1]
	s_lshl_b32 s14, s14, 12
	v_add_u32_e32 v231, s14, v233
	s_waitcnt vmcnt(0)
	ds_write_b128 v231, v[112:115]
	ds_write_b128 v231, v[116:119] offset:1024
	ds_write_b128 v231, v[120:123] offset:2048
	ds_write_b128 v231, v[124:127] offset:3072
	ds_write_b128 v231, v[80:83] offset:32768
	ds_write_b128 v231, v[84:87] offset:33792
	ds_write_b128 v231, v[88:91] offset:34816
	ds_write_b128 v231, v[92:95] offset:35840
	s_waitcnt lgkmcnt(0)
	s_barrier
	s_mov_b32 s12, 0
.Lna_loop:
	s_cmp_gt_u32 s12, 3
	s_cbranch_scc1 .Lna_top_win
	s_lshl_b32 s14, s12, 13
	v_add_u32_e32 v231, s14, v233
	ds_read_b128 v[96:99], v231
	ds_read_b128 v[100:103], v231 offset:1024
	ds_read_b128 v[104:107], v231 offset:2048
	ds_read_b128 v[108:111], v231 offset:3072
	ds_read_b128 v[68:71], v231 offset:32768
	ds_read_b128 v[76:79], v231 offset:33792
	ds_read_b128 v[64:67], v231 offset:34816
	ds_read_b128 v[72:75], v231 offset:35840
	ds_read_b128 v[112:115], v231 offset:4096
	ds_read_b128 v[116:119], v231 offset:5120
	ds_read_b128 v[120:123], v231 offset:6144
	ds_read_b128 v[124:127], v231 offset:7168
	ds_read_b128 v[80:83], v231 offset:36864
	ds_read_b128 v[84:87], v231 offset:37888
	ds_read_b128 v[88:91], v231 offset:38912
	ds_read_b128 v[92:95], v231 offset:39936
	s_waitcnt lgkmcnt(0)
	s_branch .Lna_top_done

.Lna_top_done:
	s_waitcnt vmcnt(8)
	v_mfma_f32_16x16x32_bf16 v[148:151], v[96:99], v[36:39], 0
	v_mfma_f32_16x16x32_bf16 v[152:155], v[100:103], v[36:39], 0
	v_mfma_f32_16x16x32_bf16 v[148:151], v[104:107], v[48:51], v[148:151]
	v_mfma_f32_16x16x32_bf16 v[152:155], v[108:111], v[48:51], v[152:155]
	s_cmp_gt_u32 s12, 3
	s_cbranch_scc0 .Lna_nowin_c1
	ds_read2_b32 v[156:157], v240 offset0:0 offset1:1
	ds_read2_b32 v[158:159], v240 offset0:2 offset1:3
	ds_read2_b32 v[160:161], v240 offset0:4 offset1:5
	ds_read2_b32 v[162:163], v240 offset0:6 offset1:7
	s_nop 3
	s_waitcnt lgkmcnt(0)
	v_add_u32_e32 v3, 0, v128
	v_add_f32_e32 v179, v148, v156
	v_cmp_gt_u32_e32 vcc, 16, v3
	v_add_u32_e32 v172, 1, v128
	v_add_f32_e32 v235, v149, v157
	v_cndmask_b32_e32 v148, v243, v179, vcc
	v_cmp_gt_u32_e32 vcc, 16, v172
	v_add_u32_e32 v3, 2, v128
	v_add_f32_e32 v179, v150, v158
	v_cndmask_b32_e32 v149, v243, v235, vcc
	v_cmp_gt_u32_e32 vcc, 16, v3
	v_add_u32_e32 v172, 3, v128
	v_add_f32_e32 v235, v151, v159
	v_cndmask_b32_e32 v150, v243, v179, vcc
	v_cmp_gt_u32_e32 vcc, 16, v172
	v_add_u32_e32 v3, 4, v128
	v_add_f32_e32 v179, v152, v160
	v_cndmask_b32_e32 v151, v243, v235, vcc
	v_cmp_gt_u32_e32 vcc, 16, v3
	v_add_u32_e32 v172, 5, v128
	v_add_f32_e32 v235, v153, v161
	v_cndmask_b32_e32 v152, v243, v179, vcc
	v_cmp_gt_u32_e32 vcc, 16, v172
	v_add_u32_e32 v3, 6, v128
	v_add_f32_e32 v179, v154, v162
	v_cndmask_b32_e32 v153, v243, v235, vcc
	v_cmp_gt_u32_e32 vcc, 16, v3
	v_add_u32_e32 v172, 7, v128
	v_add_f32_e32 v235, v155, v163
	v_cndmask_b32_e32 v154, v243, v179, vcc
	v_cmp_gt_u32_e32 vcc, 16, v172
	s_nop 1
	v_cndmask_b32_e32 v155, v243, v235, vcc
	s_branch .Lna_sm_c1

.Lna_skip_c2:
	v_readlane_b32 s14, v252, 23
	s_nop 3
	s_add_i32 s14, s14, -1
	s_add_i32 s0, s12, 1
	s_min_u32 s14, s0, s14
	s_cmp_lt_u32 s14, 4
	s_cbranch_scc1 .Lna_mid_skip
	s_add_i32 vcc_hi, s62, s14
	s_cmp_lt_u32 s14, 4
	s_cselect_b32 vcc_lo, s14, vcc_hi
	s_lshl_b32 vcc_lo, vcc_lo, 6
	s_mov_b32 s14, vcc_lo
	s_lshl_b32 s14, s14, 9
	s_add_u32 s0, s42, s14
	s_addc_u32 s1, s43, 0
	global_load_dwordx4 v[96:99], v174, s[0:1]
	global_load_dwordx4 v[100:103], v174, s[0:1] offset:2048
	global_load_dwordx4 v[104:107], v174, s[0:1] offset:64
	global_load_dwordx4 v[108:111], v174, s[0:1] offset:2112
	s_lshl_b32 s14, vcc_lo, 1
	s_add_u32 s0, s44, s14
	s_addc_u32 s1, s45, 0
	global_load_dwordx4 v[68:71], v175, s[0:1]
	global_load_dwordx4 v[76:79], v176, s[0:1]
	global_load_dwordx4 v[64:67], v177, s[0:1]
	global_load_dwordx4 v[72:75], v178, s[0:1]
.Lna_mid_skip:
	s_waitcnt vmcnt(8)
	s_cmp_gt_u32 s12, 3
	s_cselect_b32 s14, 1, 0
	s_cmp_eq_u32 s13, 0
	s_cselect_b32 s0, 1, 0
	s_and_b32 s14, s14, s0
	s_cmp_lg_u32 s14, 0
	s_cbranch_scc1 .Lna_skip_c3
	v_mfma_f32_16x16x32_bf16 v[148:151], v[112:115], v[36:39], 0
	v_mfma_f32_16x16x32_bf16 v[152:155], v[116:119], v[36:39], 0
	v_mfma_f32_16x16x32_bf16 v[148:151], v[120:123], v[48:51], v[148:151]
	v_mfma_f32_16x16x32_bf16 v[152:155], v[124:127], v[48:51], v[152:155]
	s_cmp_gt_u32 s12, 3
	s_cbranch_scc0 .Lna_nowin_c3
	ds_read2_b32 v[156:157], v240 offset0:32 offset1:33
	ds_read2_b32 v[158:159], v240 offset0:34 offset1:35
	ds_read2_b32 v[160:161], v240 offset0:36 offset1:37
	ds_read2_b32 v[162:163], v240 offset0:38 offset1:39
	s_nop 3
	s_waitcnt lgkmcnt(0)
	v_add_u32_e32 v3, 0, v129
	v_add_f32_e32 v179, v148, v156
	v_cmp_gt_u32_e32 vcc, 16, v3
	v_add_u32_e32 v172, 1, v129
	v_add_f32_e32 v235, v149, v157
	v_cndmask_b32_e32 v148, v243, v179, vcc
	v_cmp_gt_u32_e32 vcc, 16, v172
	v_add_u32_e32 v3, 2, v129
	v_add_f32_e32 v179, v150, v158
	v_cndmask_b32_e32 v149, v243, v235, vcc
	v_cmp_gt_u32_e32 vcc, 16, v3
	v_add_u32_e32 v172, 3, v129
	v_add_f32_e32 v235, v151, v159
	v_cndmask_b32_e32 v150, v243, v179, vcc
	v_cmp_gt_u32_e32 vcc, 16, v172
	v_add_u32_e32 v3, 4, v129
	v_add_f32_e32 v179, v152, v160
	v_cndmask_b32_e32 v151, v243, v235, vcc
	v_cmp_gt_u32_e32 vcc, 16, v3
	v_add_u32_e32 v172, 5, v129
	v_add_f32_e32 v235, v153, v161
	v_cndmask_b32_e32 v152, v243, v179, vcc
	v_cmp_gt_u32_e32 vcc, 16, v172
	v_add_u32_e32 v3, 6, v129
	v_add_f32_e32 v179, v154, v162
	v_cndmask_b32_e32 v153, v243, v235, vcc
	v_cmp_gt_u32_e32 vcc, 16, v3
	v_add_u32_e32 v172, 7, v129
	v_add_f32_e32 v235, v155, v163
	v_cndmask_b32_e32 v154, v243, v179, vcc
	v_cmp_gt_u32_e32 vcc, 16, v172
	s_nop 1
	v_cndmask_b32_e32 v155, v243, v235, vcc
	s_branch .Lna_sm_c3
